# NA epilogue: the 7 remaining silu(gate) chunks of a row prefetched next to chunk 0 (v240-253) instead of one dependent load per store step; on top of NA bias hoist + MLA epilogue prefetch
# baseline (speedup 1.0000x reference)
.LBB0_1084:
	v_mov_b32_e32 v151, v149
	v_lshl_add_u64 v[32:33], s[94:95], 0, v[150:151]
	v_lshlrev_b32_e32 v34, 1, v144
	v_mov_b32_e32 v35, v149
	v_lshl_add_u64 v[32:33], v[32:33], 0, v[34:35]
	global_load_dwordx2 v[34:35], v[32:33], off
	global_load_dwordx2 v[240:241], v[32:33], off offset:16
	global_load_dwordx2 v[242:243], v[32:33], off offset:32
	global_load_dwordx2 v[244:245], v[32:33], off offset:48
	global_load_dwordx2 v[246:247], v[32:33], off offset:64
	global_load_dwordx2 v[248:249], v[32:33], off offset:80
	global_load_dwordx2 v[250:251], v[32:33], off offset:96
	global_load_dwordx2 v[252:253], v[32:33], off offset:112
	v_rcp_f32_e32 v36, v127
	s_waitcnt vmcnt(0)
	v_lshlrev_b32_e32 v37, 16, v34
	v_mul_f32_e32 v16, v16, v36
	v_mul_f32_e32 v17, v17, v36
	v_mul_f32_e32 v18, v18, v36
	v_mul_f32_e32 v19, v19, v36
	v_and_b32_e32 v34, 0xffff0000, v34
	v_lshlrev_b32_e32 v38, 16, v35
	v_and_b32_e32 v35, 0xffff0000, v35
	v_mul_f32_e32 v16, v16, v37
	v_mul_f32_e32 v17, v17, v34
	v_mul_f32_e32 v18, v18, v38
	v_mul_f32_e32 v19, v19, v35
	v_cvt_pk_bf16_f32 v16, v16, v17
	v_cvt_pk_bf16_f32 v17, v18, v19
	v_mul_f32_e32 v20, v20, v36
	v_mul_f32_e32 v21, v21, v36
	v_mul_f32_e32 v22, v22, v36
	v_mul_f32_e32 v23, v23, v36
	global_store_dwordx2 v[32:33], v[16:17], off
	v_mul_f32_e32 v0, v0, v36
	v_mul_f32_e32 v1, v1, v36
	v_mul_f32_e32 v2, v2, v36
	v_mul_f32_e32 v3, v3, v36
	v_mul_f32_e32 v4, v4, v36
	v_mul_f32_e32 v5, v5, v36
	v_mul_f32_e32 v6, v6, v36
	v_mul_f32_e32 v7, v7, v36
	v_lshlrev_b32_e32 v16, 16, v240
	v_and_b32_e32 v17, 0xffff0000, v240
	v_lshlrev_b32_e32 v18, 16, v241
	v_and_b32_e32 v19, 0xffff0000, v241
	v_mul_f32_e32 v16, v20, v16
	v_mul_f32_e32 v17, v21, v17
	v_mul_f32_e32 v18, v22, v18
	v_mul_f32_e32 v19, v23, v19
	v_cvt_pk_bf16_f32 v16, v16, v17
	v_cvt_pk_bf16_f32 v17, v18, v19
	v_mul_f32_e32 v20, v24, v36
	v_mul_f32_e32 v21, v25, v36
	v_mul_f32_e32 v22, v26, v36
	v_mul_f32_e32 v23, v27, v36
	global_store_dwordx2 v[32:33], v[16:17], off offset:16
	v_lshlrev_b32_e32 v16, 16, v242
	v_and_b32_e32 v17, 0xffff0000, v242
	v_lshlrev_b32_e32 v18, 16, v243
	v_and_b32_e32 v19, 0xffff0000, v243
	v_mul_f32_e32 v16, v20, v16
	v_mul_f32_e32 v17, v21, v17
	v_mul_f32_e32 v18, v22, v18
	v_mul_f32_e32 v19, v23, v19
	v_cvt_pk_bf16_f32 v16, v16, v17
	v_cvt_pk_bf16_f32 v17, v18, v19
	v_mul_f32_e32 v20, v28, v36
	v_mul_f32_e32 v21, v29, v36
	v_mul_f32_e32 v22, v30, v36
	v_mul_f32_e32 v23, v31, v36
	global_store_dwordx2 v[32:33], v[16:17], off offset:32
	v_lshlrev_b32_e32 v16, 16, v244
	v_and_b32_e32 v17, 0xffff0000, v244
	v_lshlrev_b32_e32 v18, 16, v245
	v_and_b32_e32 v19, 0xffff0000, v245
	v_mul_f32_e32 v16, v20, v16
	v_mul_f32_e32 v17, v21, v17
	v_mul_f32_e32 v18, v22, v18
	v_mul_f32_e32 v19, v23, v19
	v_cvt_pk_bf16_f32 v16, v16, v17
	v_cvt_pk_bf16_f32 v17, v18, v19
	s_nop 0
	global_store_dwordx2 v[32:33], v[16:17], off offset:48
	v_lshlrev_b32_e32 v16, 16, v246
	v_and_b32_e32 v17, 0xffff0000, v246
	v_lshlrev_b32_e32 v18, 16, v247
	v_and_b32_e32 v19, 0xffff0000, v247
	v_mul_f32_e32 v0, v0, v16
	v_mul_f32_e32 v1, v1, v17
	v_mul_f32_e32 v2, v2, v18
	v_mul_f32_e32 v3, v3, v19
	v_cvt_pk_bf16_f32 v0, v0, v1
	v_cvt_pk_bf16_f32 v1, v2, v3
	s_nop 0
	global_store_dwordx2 v[32:33], v[0:1], off offset:64
	v_lshlrev_b32_e32 v0, 16, v248
	v_and_b32_e32 v1, 0xffff0000, v248
	v_lshlrev_b32_e32 v2, 16, v249
	v_and_b32_e32 v3, 0xffff0000, v249
	v_mul_f32_e32 v0, v4, v0
	v_mul_f32_e32 v1, v5, v1
	v_mul_f32_e32 v2, v6, v2
	v_mul_f32_e32 v3, v7, v3
	v_cvt_pk_bf16_f32 v0, v0, v1
	v_cvt_pk_bf16_f32 v1, v2, v3
	v_mul_f32_e32 v4, v8, v36
	v_mul_f32_e32 v5, v9, v36
	v_mul_f32_e32 v6, v10, v36
	v_mul_f32_e32 v7, v11, v36
	global_store_dwordx2 v[32:33], v[0:1], off offset:80
	v_lshlrev_b32_e32 v0, 16, v250
	v_and_b32_e32 v1, 0xffff0000, v250
	v_lshlrev_b32_e32 v2, 16, v251
	v_and_b32_e32 v3, 0xffff0000, v251
	v_mul_f32_e32 v0, v4, v0
	v_mul_f32_e32 v1, v5, v1
	v_mul_f32_e32 v2, v6, v2
	v_mul_f32_e32 v3, v7, v3
	v_cvt_pk_bf16_f32 v0, v0, v1
	v_cvt_pk_bf16_f32 v1, v2, v3
	v_mul_f32_e32 v4, v12, v36
	v_mul_f32_e32 v5, v13, v36
	global_store_dwordx2 v[32:33], v[0:1], off offset:96
	v_mul_f32_e32 v6, v14, v36
	v_mul_f32_e32 v7, v15, v36
	v_lshlrev_b32_e32 v0, 16, v252
	v_and_b32_e32 v1, 0xffff0000, v252
	v_lshlrev_b32_e32 v2, 16, v253
	v_and_b32_e32 v3, 0xffff0000, v253
	v_mul_f32_e32 v0, v4, v0
	v_mul_f32_e32 v1, v5, v1
	v_mul_f32_e32 v2, v6, v2
	v_mul_f32_e32 v3, v7, v3
	v_cvt_pk_bf16_f32 v0, v0, v1
	v_cvt_pk_bf16_f32 v1, v2, v3
	global_store_dwordx2 v[32:33], v[0:1], off offset:112
	s_barrier

.LBB0_1319:
	v_mov_b32_e32 v151, v149
	v_lshl_add_u64 v[32:33], s[94:95], 0, v[150:151]
	v_lshlrev_b32_e32 v34, 1, v144
	v_mov_b32_e32 v35, v149
	v_lshl_add_u64 v[32:33], v[32:33], 0, v[34:35]
	global_load_dwordx2 v[34:35], v[32:33], off
	global_load_dwordx2 v[240:241], v[32:33], off offset:16
	global_load_dwordx2 v[242:243], v[32:33], off offset:32
	global_load_dwordx2 v[244:245], v[32:33], off offset:48
	global_load_dwordx2 v[246:247], v[32:33], off offset:64
	global_load_dwordx2 v[248:249], v[32:33], off offset:80
	global_load_dwordx2 v[250:251], v[32:33], off offset:96
	global_load_dwordx2 v[252:253], v[32:33], off offset:112
	v_rcp_f32_e32 v36, v176
	s_mov_b64 s[70:71], 0
	v_mul_f32_e32 v16, v16, v36
	v_mul_f32_e32 v17, v17, v36
	v_mul_f32_e32 v18, v18, v36
	v_mul_f32_e32 v19, v19, v36
	v_mul_f32_e32 v20, v20, v36
	v_mul_f32_e32 v21, v21, v36
	v_mul_f32_e32 v22, v22, v36
	v_mul_f32_e32 v23, v23, v36
	v_mul_f32_e32 v0, v0, v36
	v_mul_f32_e32 v1, v1, v36
	v_mul_f32_e32 v2, v2, v36
	v_mul_f32_e32 v3, v3, v36
	v_mul_f32_e32 v4, v4, v36
	v_mul_f32_e32 v5, v5, v36
	v_mul_f32_e32 v6, v6, v36
	v_mul_f32_e32 v7, v7, v36
	s_waitcnt vmcnt(0)
	v_lshlrev_b32_e32 v37, 16, v34
	v_and_b32_e32 v34, 0xffff0000, v34
	v_lshlrev_b32_e32 v38, 16, v35
	v_and_b32_e32 v35, 0xffff0000, v35
	v_mul_f32_e32 v16, v16, v37
	v_mul_f32_e32 v17, v17, v34
	v_mul_f32_e32 v18, v18, v38
	v_mul_f32_e32 v19, v19, v35
	v_cvt_pk_bf16_f32 v16, v16, v17
	v_cvt_pk_bf16_f32 v17, v18, v19
	s_nop 0
	global_store_dwordx2 v[32:33], v[16:17], off
	v_lshlrev_b32_e32 v16, 16, v240
	v_and_b32_e32 v17, 0xffff0000, v240
	v_lshlrev_b32_e32 v18, 16, v241
	v_and_b32_e32 v19, 0xffff0000, v241
	v_mul_f32_e32 v16, v20, v16
	v_mul_f32_e32 v17, v21, v17
	v_mul_f32_e32 v18, v22, v18
	v_mul_f32_e32 v19, v23, v19
	v_cvt_pk_bf16_f32 v16, v16, v17
	v_cvt_pk_bf16_f32 v17, v18, v19
	v_mul_f32_e32 v20, v24, v36
	v_mul_f32_e32 v21, v25, v36
	v_mul_f32_e32 v22, v26, v36
	v_mul_f32_e32 v23, v27, v36
	global_store_dwordx2 v[32:33], v[16:17], off offset:16
	v_lshlrev_b32_e32 v16, 16, v242
	v_and_b32_e32 v17, 0xffff0000, v242
	v_lshlrev_b32_e32 v18, 16, v243
	v_and_b32_e32 v19, 0xffff0000, v243
	v_mul_f32_e32 v16, v20, v16
	v_mul_f32_e32 v17, v21, v17
	v_mul_f32_e32 v18, v22, v18
	v_mul_f32_e32 v19, v23, v19
	v_cvt_pk_bf16_f32 v16, v16, v17
	v_cvt_pk_bf16_f32 v17, v18, v19
	v_mul_f32_e32 v20, v28, v36
	v_mul_f32_e32 v21, v29, v36
	v_mul_f32_e32 v22, v30, v36
	v_mul_f32_e32 v23, v31, v36
	global_store_dwordx2 v[32:33], v[16:17], off offset:32
	v_lshlrev_b32_e32 v16, 16, v244
	v_and_b32_e32 v17, 0xffff0000, v244
	v_lshlrev_b32_e32 v18, 16, v245
	v_and_b32_e32 v19, 0xffff0000, v245
	v_mul_f32_e32 v16, v20, v16
	v_mul_f32_e32 v17, v21, v17
	v_mul_f32_e32 v18, v22, v18
	v_mul_f32_e32 v19, v23, v19
	v_cvt_pk_bf16_f32 v16, v16, v17
	v_cvt_pk_bf16_f32 v17, v18, v19
	s_nop 0
	global_store_dwordx2 v[32:33], v[16:17], off offset:48
	v_lshlrev_b32_e32 v16, 16, v246
	v_and_b32_e32 v17, 0xffff0000, v246
	v_lshlrev_b32_e32 v18, 16, v247
	v_and_b32_e32 v19, 0xffff0000, v247
	v_mul_f32_e32 v0, v0, v16
	v_mul_f32_e32 v1, v1, v17
	v_mul_f32_e32 v2, v2, v18
	v_mul_f32_e32 v3, v3, v19
	v_cvt_pk_bf16_f32 v0, v0, v1
	v_cvt_pk_bf16_f32 v1, v2, v3
	s_nop 0
	global_store_dwordx2 v[32:33], v[0:1], off offset:64
	v_lshlrev_b32_e32 v0, 16, v248
	v_and_b32_e32 v1, 0xffff0000, v248
	v_lshlrev_b32_e32 v2, 16, v249
	v_and_b32_e32 v3, 0xffff0000, v249
	v_mul_f32_e32 v0, v4, v0
	v_mul_f32_e32 v1, v5, v1
	v_mul_f32_e32 v2, v6, v2
	v_mul_f32_e32 v3, v7, v3
	v_cvt_pk_bf16_f32 v0, v0, v1
	v_cvt_pk_bf16_f32 v1, v2, v3
	v_mul_f32_e32 v4, v8, v36
	v_mul_f32_e32 v5, v9, v36
	v_mul_f32_e32 v6, v10, v36
	v_mul_f32_e32 v7, v11, v36
	global_store_dwordx2 v[32:33], v[0:1], off offset:80
	v_lshlrev_b32_e32 v0, 16, v250
	v_and_b32_e32 v1, 0xffff0000, v250
	v_lshlrev_b32_e32 v2, 16, v251
	v_and_b32_e32 v3, 0xffff0000, v251
	v_mul_f32_e32 v0, v4, v0
	v_mul_f32_e32 v1, v5, v1
	v_mul_f32_e32 v2, v6, v2
	v_mul_f32_e32 v3, v7, v3
	v_cvt_pk_bf16_f32 v0, v0, v1
	v_cvt_pk_bf16_f32 v1, v2, v3
	v_mul_f32_e32 v4, v12, v36
	v_mul_f32_e32 v5, v13, v36
	global_store_dwordx2 v[32:33], v[0:1], off offset:96
	v_mul_f32_e32 v6, v14, v36
	v_mul_f32_e32 v7, v15, v36
	v_lshlrev_b32_e32 v0, 16, v252
	v_and_b32_e32 v1, 0xffff0000, v252
	v_lshlrev_b32_e32 v2, 16, v253
	v_and_b32_e32 v3, 0xffff0000, v253
	v_mul_f32_e32 v0, v4, v0
	v_mul_f32_e32 v1, v5, v1
	v_mul_f32_e32 v2, v6, v2
	v_mul_f32_e32 v3, v7, v3
	v_cvt_pk_bf16_f32 v0, v0, v1
	v_cvt_pk_bf16_f32 v1, v2, v3
	global_store_dwordx2 v[32:33], v[0:1], off offset:112
	s_barrier

.LBB0_1559:
	v_exp_f32_e32 v52, v64
	v_exp_f32_e32 v53, v65
	v_exp_f32_e32 v54, v66
	v_exp_f32_e32 v55, v67
	v_exp_f32_e32 v56, v68
	v_add_f32_e32 v49, v49, v50
	v_exp_f32_e32 v50, v32
	v_add_f32_e32 v32, 0, v52
	v_exp_f32_e32 v57, v69
	v_add_f32_e32 v32, v53, v32
	v_exp_f32_e32 v58, v70
	v_add_f32_e32 v32, v54, v32
	v_exp_f32_e32 v59, v71
	v_add_f32_e32 v32, v55, v32
	v_exp_f32_e32 v60, v72
	v_add_f32_e32 v32, v56, v32
	v_sub_f32_e32 v51, 0xf149f2ca, v111
	v_exp_f32_e32 v61, v73
	v_add_f32_e32 v32, v57, v32
	v_exp_f32_e32 v51, v51
	v_exp_f32_e32 v62, v74
	v_add_f32_e32 v32, v58, v32
	v_exp_f32_e32 v63, v75
	v_add_f32_e32 v32, v59, v32
	v_exp_f32_e32 v64, v76
	v_add_f32_e32 v32, v60, v32
	v_exp_f32_e32 v65, v77
	v_add_f32_e32 v32, v61, v32
	v_exp_f32_e32 v66, v78
	v_mul_f32_e32 v51, 0, v51
	v_add_f32_e32 v32, v62, v32
	v_exp_f32_e32 v67, v79
	v_add_f32_e32 v68, v115, v119
	v_cndmask_b32_e64 v51, v51, 0, s[2:3]
	v_add_f32_e32 v32, v63, v32
	v_add_f32_e32 v51, v51, v68
	v_add_f32_e32 v68, v121, v122
	v_add_f32_e32 v32, v64, v32
	v_fmac_f32_e32 v68, v51, v106
	v_exp_f32_e32 v51, v33
	v_add_f32_e32 v32, v65, v32
	v_fmac_f32_e32 v49, v68, v118
	v_exp_f32_e32 v68, v34
	v_add_f32_e32 v32, v66, v32
	v_exp_f32_e32 v69, v35
	v_add_f32_e32 v32, v67, v32
	v_exp_f32_e32 v70, v36
	v_add_f32_e32 v32, v50, v32
	v_exp_f32_e32 v71, v37
	v_add_f32_e32 v32, v51, v32
	v_exp_f32_e32 v72, v38
	v_add_f32_e32 v32, v68, v32
	v_exp_f32_e32 v73, v39
	v_add_f32_e32 v32, v69, v32
	v_exp_f32_e32 v74, v40
	v_add_f32_e32 v32, v70, v32
	v_exp_f32_e32 v75, v41
	v_add_f32_e32 v32, v71, v32
	v_exp_f32_e32 v76, v42
	v_add_f32_e32 v32, v72, v32
	v_exp_f32_e32 v77, v43
	v_add_f32_e32 v32, v73, v32
	v_exp_f32_e32 v78, v44
	v_add_f32_e32 v32, v74, v32
	v_exp_f32_e32 v79, v45
	v_add_f32_e32 v32, v75, v32
	v_exp_f32_e32 v80, v46
	v_add_f32_e32 v32, v76, v32
	v_exp_f32_e32 v47, v47
	v_add_f32_e32 v32, v77, v32
	v_add_f32_e32 v32, v78, v32
	v_add_f32_e32 v32, v79, v32
	v_add_f32_e32 v32, v80, v32
	v_add_f32_e32 v32, v47, v32
	v_mov_b32_e32 v33, v32
	s_nop 1
	v_permlane32_swap_b32_e32 v32, v33
	v_add_f32_e32 v81, v32, v33
	v_fmac_f32_e32 v81, v49, v48
	v_cvt_pk_bf16_f32 v32, v52, v53
	v_cvt_pk_bf16_f32 v33, v54, v55
	v_cvt_pk_bf16_f32 v34, v56, v57
	v_cvt_pk_bf16_f32 v35, v58, v59
	v_cvt_pk_bf16_f32 v36, v60, v61
	v_cvt_pk_bf16_f32 v37, v62, v63
	v_cvt_pk_bf16_f32 v38, v64, v65
	v_cvt_pk_bf16_f32 v39, v66, v67
	v_cvt_pk_bf16_f32 v40, v50, v51
	v_cvt_pk_bf16_f32 v41, v68, v69
	v_cvt_pk_bf16_f32 v42, v70, v71
	v_cvt_pk_bf16_f32 v43, v72, v73
	v_cvt_pk_bf16_f32 v44, v74, v75
	v_cvt_pk_bf16_f32 v45, v76, v77
	v_cvt_pk_bf16_f32 v46, v78, v79
	v_cvt_pk_bf16_f32 v47, v80, v47
	ds_read_b64_tr_b16 v[48:49], v125 offset:0
	ds_read_b64_tr_b16 v[50:51], v125 offset:0x400
	ds_read_b64_tr_b16 v[52:53], v125 offset:0x800
	ds_read_b64_tr_b16 v[54:55], v125 offset:0xc00
	ds_read_b64_tr_b16 v[56:57], v125 offset:0x1000
	ds_read_b64_tr_b16 v[58:59], v125 offset:0x1400
	ds_read_b64_tr_b16 v[60:61], v125 offset:0x1800
	ds_read_b64_tr_b16 v[62:63], v125 offset:0x1c00
	s_waitcnt lgkmcnt(0)
	s_nop 0
	v_mfma_f32_32x32x16_bf16 v[16:31], v[48:51], v[32:35], v[16:31]
	ds_read_b64_tr_b16 v[48:49], v125 offset:0x200
	ds_read_b64_tr_b16 v[50:51], v125 offset:0x600
	v_mfma_f32_32x32x16_bf16 v[16:31], v[52:55], v[36:39], v[16:31]
	ds_read_b64_tr_b16 v[52:53], v125 offset:0xa00
	ds_read_b64_tr_b16 v[54:55], v125 offset:0xe00
	v_mfma_f32_32x32x16_bf16 v[16:31], v[56:59], v[40:43], v[16:31]
	ds_read_b64_tr_b16 v[56:57], v125 offset:0x1200
	ds_read_b64_tr_b16 v[58:59], v125 offset:0x1600
	ds_read_b64_tr_b16 v[64:65], v125 offset:0x1a00
	ds_read_b64_tr_b16 v[66:67], v125 offset:0x1e00
	s_waitcnt lgkmcnt(0)
	v_mfma_f32_32x32x16_bf16 v[16:31], v[60:63], v[44:47], v[16:31]
	v_lshlrev_b32_e32 v106, 1, v104
	v_lshl_add_u64 v[60:61], s[0:1], 0, v[106:107]
	v_lshlrev_b32_e32 v106, 1, v144
	v_lshl_add_u64 v[60:61], v[60:61], 0, v[106:107]
	global_load_dwordx2 v[62:63], v[60:61], off
	global_load_dwordx2 v[240:241], v[60:61], off offset:16
	global_load_dwordx2 v[242:243], v[60:61], off offset:32
	global_load_dwordx2 v[244:245], v[60:61], off offset:48
	global_load_dwordx2 v[246:247], v[60:61], off offset:64
	global_load_dwordx2 v[248:249], v[60:61], off offset:80
	global_load_dwordx2 v[250:251], v[60:61], off offset:96
	global_load_dwordx2 v[252:253], v[60:61], off offset:112
	v_rcp_f32_e32 v68, v81
	v_mfma_f32_32x32x16_bf16 v[0:15], v[48:51], v[32:35], v[0:15]
	s_nop 4
	v_mul_f32_e32 v16, v68, v16
	v_mul_f32_e32 v17, v68, v17
	v_mul_f32_e32 v18, v68, v18
	v_mul_f32_e32 v19, v68, v19
	v_mul_f32_e32 v20, v68, v20
	v_mul_f32_e32 v21, v68, v21
	v_mul_f32_e32 v22, v68, v22
	v_mul_f32_e32 v23, v68, v23
	v_mfma_f32_32x32x16_bf16 v[0:15], v[52:55], v[36:39], v[0:15]
	s_waitcnt vmcnt(0)
	v_lshlrev_b32_e32 v69, 16, v62
	v_and_b32_e32 v62, 0xffff0000, v62
	v_lshlrev_b32_e32 v70, 16, v63
	v_and_b32_e32 v63, 0xffff0000, v63
	v_mul_f32_e32 v16, v16, v69
	v_mul_f32_e32 v17, v17, v62
	v_mul_f32_e32 v18, v18, v70
	v_mul_f32_e32 v19, v19, v63
	v_cvt_pk_bf16_f32 v16, v16, v17
	v_cvt_pk_bf16_f32 v17, v18, v19
	v_mfma_f32_32x32x16_bf16 v[0:15], v[56:59], v[40:43], v[0:15]
	global_store_dwordx2 v[60:61], v[16:17], off
	v_lshlrev_b32_e32 v16, 16, v240
	v_and_b32_e32 v17, 0xffff0000, v240
	v_lshlrev_b32_e32 v18, 16, v241
	v_and_b32_e32 v19, 0xffff0000, v241
	v_mul_f32_e32 v16, v20, v16
	v_mul_f32_e32 v17, v21, v17
	v_mul_f32_e32 v18, v22, v18
	v_mul_f32_e32 v19, v23, v19
	v_cvt_pk_bf16_f32 v16, v16, v17
	v_cvt_pk_bf16_f32 v17, v18, v19
	v_mul_f32_e32 v20, v68, v24
	v_mul_f32_e32 v21, v68, v25
	v_mul_f32_e32 v22, v68, v26
	v_mul_f32_e32 v23, v68, v27
	global_store_dwordx2 v[60:61], v[16:17], off offset:16
	v_mfma_f32_32x32x16_bf16 v[0:15], v[64:67], v[44:47], v[0:15]
	v_lshlrev_b32_e32 v16, 16, v242
	v_and_b32_e32 v17, 0xffff0000, v242
	v_lshlrev_b32_e32 v18, 16, v243
	v_and_b32_e32 v19, 0xffff0000, v243
	v_mul_f32_e32 v16, v20, v16
	v_mul_f32_e32 v17, v21, v17
	v_mul_f32_e32 v18, v22, v18
	v_mul_f32_e32 v19, v23, v19
	v_cvt_pk_bf16_f32 v16, v16, v17
	v_cvt_pk_bf16_f32 v17, v18, v19
	v_mul_f32_e32 v20, v68, v28
	v_mul_f32_e32 v21, v68, v29
	v_mul_f32_e32 v22, v68, v30
	v_mul_f32_e32 v23, v68, v31
	global_store_dwordx2 v[60:61], v[16:17], off offset:32
	v_mul_f32_e32 v0, v68, v0
	v_mul_f32_e32 v1, v68, v1
	v_mul_f32_e32 v2, v68, v2
	v_mul_f32_e32 v3, v68, v3
	v_mul_f32_e32 v4, v68, v4
	v_mul_f32_e32 v5, v68, v5
	v_mul_f32_e32 v6, v68, v6
	v_mul_f32_e32 v7, v68, v7
	v_lshlrev_b32_e32 v16, 16, v244
	v_and_b32_e32 v17, 0xffff0000, v244
	v_lshlrev_b32_e32 v18, 16, v245
	v_and_b32_e32 v19, 0xffff0000, v245
	v_mul_f32_e32 v16, v20, v16
	v_mul_f32_e32 v17, v21, v17
	v_mul_f32_e32 v18, v22, v18
	v_mul_f32_e32 v19, v23, v19
	v_cvt_pk_bf16_f32 v16, v16, v17
	v_cvt_pk_bf16_f32 v17, v18, v19
	s_nop 0
	global_store_dwordx2 v[60:61], v[16:17], off offset:48
	v_lshlrev_b32_e32 v16, 16, v246
	v_and_b32_e32 v17, 0xffff0000, v246
	v_lshlrev_b32_e32 v18, 16, v247
	v_and_b32_e32 v19, 0xffff0000, v247
	v_mul_f32_e32 v0, v0, v16
	v_mul_f32_e32 v1, v1, v17
	v_mul_f32_e32 v2, v2, v18
	v_mul_f32_e32 v3, v3, v19
	v_cvt_pk_bf16_f32 v0, v0, v1
	v_cvt_pk_bf16_f32 v1, v2, v3
	s_nop 0
	global_store_dwordx2 v[60:61], v[0:1], off offset:64
	v_lshlrev_b32_e32 v0, 16, v248
	v_and_b32_e32 v1, 0xffff0000, v248
	v_lshlrev_b32_e32 v2, 16, v249
	v_and_b32_e32 v3, 0xffff0000, v249
	v_mul_f32_e32 v0, v4, v0
	v_mul_f32_e32 v1, v5, v1
	v_mul_f32_e32 v2, v6, v2
	v_mul_f32_e32 v3, v7, v3
	v_cvt_pk_bf16_f32 v0, v0, v1
	v_cvt_pk_bf16_f32 v1, v2, v3
	v_mul_f32_e32 v4, v68, v8
	v_mul_f32_e32 v5, v68, v9
	v_mul_f32_e32 v6, v68, v10
	v_mul_f32_e32 v7, v68, v11
	global_store_dwordx2 v[60:61], v[0:1], off offset:80
	v_lshlrev_b32_e32 v0, 16, v250
	v_and_b32_e32 v1, 0xffff0000, v250
	v_lshlrev_b32_e32 v2, 16, v251
	v_and_b32_e32 v3, 0xffff0000, v251
	v_mul_f32_e32 v0, v4, v0
	v_mul_f32_e32 v1, v5, v1
	v_mul_f32_e32 v2, v6, v2
	v_mul_f32_e32 v3, v7, v3
	v_cvt_pk_bf16_f32 v0, v0, v1
	v_cvt_pk_bf16_f32 v1, v2, v3
	v_mul_f32_e32 v4, v68, v12
	v_mul_f32_e32 v5, v68, v13
	global_store_dwordx2 v[60:61], v[0:1], off offset:96
	v_mul_f32_e32 v6, v68, v14
	v_mul_f32_e32 v7, v68, v15
	v_lshlrev_b32_e32 v0, 16, v252
	v_and_b32_e32 v1, 0xffff0000, v252
	v_lshlrev_b32_e32 v2, 16, v253
	v_and_b32_e32 v3, 0xffff0000, v253
	v_mul_f32_e32 v0, v4, v0
	v_mul_f32_e32 v1, v5, v1
	v_mul_f32_e32 v2, v6, v2
	v_mul_f32_e32 v3, v7, v3
	v_cvt_pk_bf16_f32 v0, v0, v1
	v_cvt_pk_bf16_f32 v1, v2, v3
	global_store_dwordx2 v[60:61], v[0:1], off offset:112
	s_barrier

.LBB0_1571:
	v_exp_f32_e32 v52, v64
	v_exp_f32_e32 v53, v65
	v_exp_f32_e32 v54, v66
	v_exp_f32_e32 v55, v67
	v_exp_f32_e32 v56, v68
	v_add_f32_e32 v49, v49, v50
	v_exp_f32_e32 v50, v32
	v_add_f32_e32 v32, 0, v52
	v_exp_f32_e32 v57, v69
	v_add_f32_e32 v32, v53, v32
	v_exp_f32_e32 v58, v70
	v_add_f32_e32 v32, v54, v32
	v_exp_f32_e32 v59, v71
	v_add_f32_e32 v32, v55, v32
	v_exp_f32_e32 v60, v72
	v_add_f32_e32 v32, v56, v32
	v_sub_f32_e32 v51, 0xf149f2ca, v111
	v_exp_f32_e32 v61, v73
	v_add_f32_e32 v32, v57, v32
	v_exp_f32_e32 v51, v51
	v_exp_f32_e32 v62, v74
	v_add_f32_e32 v32, v58, v32
	v_exp_f32_e32 v63, v75
	v_add_f32_e32 v32, v59, v32
	v_exp_f32_e32 v64, v76
	v_add_f32_e32 v32, v60, v32
	v_exp_f32_e32 v65, v77
	v_add_f32_e32 v32, v61, v32
	v_exp_f32_e32 v66, v78
	v_mul_f32_e32 v51, 0, v51
	v_add_f32_e32 v32, v62, v32
	v_exp_f32_e32 v67, v79
	v_add_f32_e32 v68, v115, v133
	v_cndmask_b32_e64 v51, v51, 0, s[2:3]
	v_add_f32_e32 v32, v63, v32
	v_add_f32_e32 v51, v51, v68
	v_add_f32_e32 v68, v135, v136
	v_add_f32_e32 v32, v64, v32
	v_fmac_f32_e32 v68, v51, v106
	v_exp_f32_e32 v51, v33
	v_add_f32_e32 v32, v65, v32
	v_fmac_f32_e32 v49, v68, v124
	v_exp_f32_e32 v68, v34
	v_add_f32_e32 v32, v66, v32
	v_exp_f32_e32 v69, v35
	v_add_f32_e32 v32, v67, v32
	v_exp_f32_e32 v70, v36
	v_add_f32_e32 v32, v50, v32
	v_exp_f32_e32 v71, v37
	v_add_f32_e32 v32, v51, v32
	v_exp_f32_e32 v72, v38
	v_add_f32_e32 v32, v68, v32
	v_exp_f32_e32 v73, v39
	v_add_f32_e32 v32, v69, v32
	v_exp_f32_e32 v74, v40
	v_add_f32_e32 v32, v70, v32
	v_exp_f32_e32 v75, v41
	v_add_f32_e32 v32, v71, v32
	v_exp_f32_e32 v76, v42
	v_add_f32_e32 v32, v72, v32
	v_exp_f32_e32 v77, v43
	v_add_f32_e32 v32, v73, v32
	v_exp_f32_e32 v78, v44
	v_add_f32_e32 v32, v74, v32
	v_exp_f32_e32 v79, v45
	v_add_f32_e32 v32, v75, v32
	v_exp_f32_e32 v80, v46
	v_add_f32_e32 v32, v76, v32
	v_exp_f32_e32 v47, v47
	v_add_f32_e32 v32, v77, v32
	v_add_f32_e32 v32, v78, v32
	v_add_f32_e32 v32, v79, v32
	v_add_f32_e32 v32, v80, v32
	v_add_f32_e32 v32, v47, v32
	v_mov_b32_e32 v33, v32
	s_nop 1
	v_permlane32_swap_b32_e32 v32, v33
	v_add_f32_e32 v81, v32, v33
	v_fmac_f32_e32 v81, v49, v48
	v_cvt_pk_bf16_f32 v32, v52, v53
	v_cvt_pk_bf16_f32 v33, v54, v55
	v_cvt_pk_bf16_f32 v34, v56, v57
	v_cvt_pk_bf16_f32 v35, v58, v59
	v_cvt_pk_bf16_f32 v36, v60, v61
	v_cvt_pk_bf16_f32 v37, v62, v63
	v_cvt_pk_bf16_f32 v38, v64, v65
	v_cvt_pk_bf16_f32 v39, v66, v67
	v_cvt_pk_bf16_f32 v40, v50, v51
	v_cvt_pk_bf16_f32 v41, v68, v69
	v_cvt_pk_bf16_f32 v42, v70, v71
	v_cvt_pk_bf16_f32 v43, v72, v73
	v_cvt_pk_bf16_f32 v44, v74, v75
	v_cvt_pk_bf16_f32 v45, v76, v77
	v_cvt_pk_bf16_f32 v46, v78, v79
	v_cvt_pk_bf16_f32 v47, v80, v47
	ds_read_b64_tr_b16 v[48:49], v125 offset:0
	ds_read_b64_tr_b16 v[50:51], v125 offset:0x400
	ds_read_b64_tr_b16 v[52:53], v125 offset:0x800
	ds_read_b64_tr_b16 v[54:55], v125 offset:0xc00
	ds_read_b64_tr_b16 v[56:57], v125 offset:0x1000
	ds_read_b64_tr_b16 v[58:59], v125 offset:0x1400
	ds_read_b64_tr_b16 v[60:61], v125 offset:0x1800
	ds_read_b64_tr_b16 v[62:63], v125 offset:0x1c00
	s_waitcnt lgkmcnt(0)
	s_nop 0
	v_mfma_f32_32x32x16_bf16 v[16:31], v[48:51], v[32:35], v[16:31]
	ds_read_b64_tr_b16 v[48:49], v125 offset:0x200
	ds_read_b64_tr_b16 v[50:51], v125 offset:0x600
	v_mfma_f32_32x32x16_bf16 v[16:31], v[52:55], v[36:39], v[16:31]
	ds_read_b64_tr_b16 v[52:53], v125 offset:0xa00
	ds_read_b64_tr_b16 v[54:55], v125 offset:0xe00
	v_mfma_f32_32x32x16_bf16 v[16:31], v[56:59], v[40:43], v[16:31]
	ds_read_b64_tr_b16 v[56:57], v125 offset:0x1200
	ds_read_b64_tr_b16 v[58:59], v125 offset:0x1600
	ds_read_b64_tr_b16 v[64:65], v125 offset:0x1a00
	ds_read_b64_tr_b16 v[66:67], v125 offset:0x1e00
	s_waitcnt lgkmcnt(0)
	v_mfma_f32_32x32x16_bf16 v[16:31], v[60:63], v[44:47], v[16:31]
	v_lshlrev_b32_e32 v106, 1, v104
	v_lshl_add_u64 v[60:61], s[0:1], 0, v[106:107]
	v_lshlrev_b32_e32 v106, 1, v144
	v_lshl_add_u64 v[60:61], v[60:61], 0, v[106:107]
	global_load_dwordx2 v[62:63], v[60:61], off
	global_load_dwordx2 v[240:241], v[60:61], off offset:16
	global_load_dwordx2 v[242:243], v[60:61], off offset:32
	global_load_dwordx2 v[244:245], v[60:61], off offset:48
	global_load_dwordx2 v[246:247], v[60:61], off offset:64
	global_load_dwordx2 v[248:249], v[60:61], off offset:80
	global_load_dwordx2 v[250:251], v[60:61], off offset:96
	global_load_dwordx2 v[252:253], v[60:61], off offset:112
	v_rcp_f32_e32 v68, v81
	v_mfma_f32_32x32x16_bf16 v[0:15], v[48:51], v[32:35], v[0:15]
	s_mov_b64 s[2:3], 0
	s_nop 3
	v_mul_f32_e32 v16, v68, v16
	v_mul_f32_e32 v17, v68, v17
	v_mul_f32_e32 v18, v68, v18
	v_mul_f32_e32 v19, v68, v19
	v_mul_f32_e32 v20, v68, v20
	v_mul_f32_e32 v21, v68, v21
	v_mul_f32_e32 v22, v68, v22
	v_mul_f32_e32 v23, v68, v23
	v_mfma_f32_32x32x16_bf16 v[0:15], v[52:55], v[36:39], v[0:15]
	s_waitcnt vmcnt(0)
	v_lshlrev_b32_e32 v69, 16, v62
	v_and_b32_e32 v62, 0xffff0000, v62
	v_lshlrev_b32_e32 v70, 16, v63
	v_and_b32_e32 v63, 0xffff0000, v63
	v_mul_f32_e32 v16, v16, v69
	v_mul_f32_e32 v17, v17, v62
	v_mul_f32_e32 v18, v18, v70
	v_mul_f32_e32 v19, v19, v63
	v_cvt_pk_bf16_f32 v16, v16, v17
	v_cvt_pk_bf16_f32 v17, v18, v19
	v_mfma_f32_32x32x16_bf16 v[0:15], v[56:59], v[40:43], v[0:15]
	global_store_dwordx2 v[60:61], v[16:17], off
	v_lshlrev_b32_e32 v16, 16, v240
	v_and_b32_e32 v17, 0xffff0000, v240
	v_lshlrev_b32_e32 v18, 16, v241
	v_and_b32_e32 v19, 0xffff0000, v241
	v_mul_f32_e32 v16, v20, v16
	v_mul_f32_e32 v17, v21, v17
	v_mul_f32_e32 v18, v22, v18
	v_mul_f32_e32 v19, v23, v19
	v_cvt_pk_bf16_f32 v16, v16, v17
	v_cvt_pk_bf16_f32 v17, v18, v19
	v_mul_f32_e32 v20, v68, v24
	v_mul_f32_e32 v21, v68, v25
	v_mul_f32_e32 v22, v68, v26
	v_mul_f32_e32 v23, v68, v27
	global_store_dwordx2 v[60:61], v[16:17], off offset:16
	v_mfma_f32_32x32x16_bf16 v[0:15], v[64:67], v[44:47], v[0:15]
	v_lshlrev_b32_e32 v16, 16, v242
	v_and_b32_e32 v17, 0xffff0000, v242
	v_lshlrev_b32_e32 v18, 16, v243
	v_and_b32_e32 v19, 0xffff0000, v243
	v_mul_f32_e32 v16, v20, v16
	v_mul_f32_e32 v17, v21, v17
	v_mul_f32_e32 v18, v22, v18
	v_mul_f32_e32 v19, v23, v19
	v_cvt_pk_bf16_f32 v16, v16, v17
	v_cvt_pk_bf16_f32 v17, v18, v19
	v_mul_f32_e32 v20, v68, v28
	v_mul_f32_e32 v21, v68, v29
	v_mul_f32_e32 v22, v68, v30
	v_mul_f32_e32 v23, v68, v31
	global_store_dwordx2 v[60:61], v[16:17], off offset:32
	v_mul_f32_e32 v0, v68, v0
	v_mul_f32_e32 v1, v68, v1
	v_mul_f32_e32 v2, v68, v2
	v_mul_f32_e32 v3, v68, v3
	v_mul_f32_e32 v4, v68, v4
	v_mul_f32_e32 v5, v68, v5
	v_mul_f32_e32 v6, v68, v6
	v_mul_f32_e32 v7, v68, v7
	v_lshlrev_b32_e32 v16, 16, v244
	v_and_b32_e32 v17, 0xffff0000, v244
	v_lshlrev_b32_e32 v18, 16, v245
	v_and_b32_e32 v19, 0xffff0000, v245
	v_mul_f32_e32 v16, v20, v16
	v_mul_f32_e32 v17, v21, v17
	v_mul_f32_e32 v18, v22, v18
	v_mul_f32_e32 v19, v23, v19
	v_cvt_pk_bf16_f32 v16, v16, v17
	v_cvt_pk_bf16_f32 v17, v18, v19
	s_nop 0
	global_store_dwordx2 v[60:61], v[16:17], off offset:48
	v_lshlrev_b32_e32 v16, 16, v246
	v_and_b32_e32 v17, 0xffff0000, v246
	v_lshlrev_b32_e32 v18, 16, v247
	v_and_b32_e32 v19, 0xffff0000, v247
	v_mul_f32_e32 v0, v0, v16
	v_mul_f32_e32 v1, v1, v17
	v_mul_f32_e32 v2, v2, v18
	v_mul_f32_e32 v3, v3, v19
	v_cvt_pk_bf16_f32 v0, v0, v1
	v_cvt_pk_bf16_f32 v1, v2, v3
	s_nop 0
	global_store_dwordx2 v[60:61], v[0:1], off offset:64
	v_lshlrev_b32_e32 v0, 16, v248
	v_and_b32_e32 v1, 0xffff0000, v248
	v_lshlrev_b32_e32 v2, 16, v249
	v_and_b32_e32 v3, 0xffff0000, v249
	v_mul_f32_e32 v0, v4, v0
	v_mul_f32_e32 v1, v5, v1
	v_mul_f32_e32 v2, v6, v2
	v_mul_f32_e32 v3, v7, v3
	v_cvt_pk_bf16_f32 v0, v0, v1
	v_cvt_pk_bf16_f32 v1, v2, v3
	v_mul_f32_e32 v4, v68, v8
	v_mul_f32_e32 v5, v68, v9
	v_mul_f32_e32 v6, v68, v10
	v_mul_f32_e32 v7, v68, v11
	global_store_dwordx2 v[60:61], v[0:1], off offset:80
	v_lshlrev_b32_e32 v0, 16, v250
	v_and_b32_e32 v1, 0xffff0000, v250
	v_lshlrev_b32_e32 v2, 16, v251
	v_and_b32_e32 v3, 0xffff0000, v251
	v_mul_f32_e32 v0, v4, v0
	v_mul_f32_e32 v1, v5, v1
	v_mul_f32_e32 v2, v6, v2
	v_mul_f32_e32 v3, v7, v3
	v_cvt_pk_bf16_f32 v0, v0, v1
	v_cvt_pk_bf16_f32 v1, v2, v3
	v_mul_f32_e32 v4, v68, v12
	v_mul_f32_e32 v5, v68, v13
	global_store_dwordx2 v[60:61], v[0:1], off offset:96
	v_mul_f32_e32 v6, v68, v14
	v_mul_f32_e32 v7, v68, v15
	v_lshlrev_b32_e32 v0, 16, v252
	v_and_b32_e32 v1, 0xffff0000, v252
	v_lshlrev_b32_e32 v2, 16, v253
	v_and_b32_e32 v3, 0xffff0000, v253
	v_mul_f32_e32 v0, v4, v0
	v_mul_f32_e32 v1, v5, v1
	v_mul_f32_e32 v2, v6, v2
	v_mul_f32_e32 v3, v7, v3
	v_cvt_pk_bf16_f32 v0, v0, v1
	v_cvt_pk_bf16_f32 v1, v2, v3
	global_store_dwordx2 v[60:61], v[0:1], off offset:112
	s_barrier
